# combine phase: hoist loop-invariant P[S/2] scattered ushort loads out of the item loop (8 loads once, v_cndmask select by batch)
# speedup vs baseline: 1.0093x; 1.0093x over previous
; __device__ __forceinline__ int obid() { int b = (int)blockIdx.x; asm volatile("" : "+s"(b)); return b; }
; __device__ __forceinline__ int otid() { int t; asm volatile("v_mov_b32 %0, %1" : "=v"(t) : "v"(threadIdx.x)); return t; }
; __device__ __forceinline__ KParams kparams() { KParams k = (KParams)__builtin_amdgcn_kernarg_segment_ptr(); asm volatile("" : "+s"(k)); return k; }
; __device__ __forceinline__ float bf2f(bf16 b) { return __uint_as_float((unsigned)b << 16); }
; __device__ __forceinline__ void ph_combine(const Params& p_) {
;     const Params p = *kparams(); (void)p_;
;     const float* Ce = (const float*)(p.ws + WS_PART); const float* So = Ce + (size_t)2 * 2304 * 512;
;     bf16* CAT = (bf16*)(p.ws + WS_CAT); const bf16* Z = (const bf16*)(p.ws + WS_Z); const bf16* PQ = (const bf16*)(p.ws + WS_PQT);
;     const int nth = gridDim.x * NTHR;
;     for (int e0 = obid() * NTHR + otid(); e0 < MTOK * DG / 4; e0 += 2 * nth) {
;         f32x4 ce[2], so[2]; u32x2 gz[2]; float pv[2][4]; int rowv[2], c4v[2], kv[2]; bool use_so[2], act[2];
; #pragma unroll
;         for (int u = 0; u < 2; ++u) { const int e = e0 + u * nth; act[u] = e < MTOK * DG / 4; const int ee = act[u] ? e : e0;
;             const int row = ee >> 7, c4 = (ee & 127) * 4, b = row >> 12, k = row & 4095, kk = (k <= 2048) ? k : 4096 - k;
;             rowv[u] = row; c4v[u] = c4; kv[u] = k; use_so[u] = (kk != 0 && kk != 2048);
;             ce[u] = (kk == 2048) ? *(const f32x4*)(Ce + (size_t)(2 * 2304 + 2 * 2048) * 512 + b * 512 + c4) : *(const f32x4*)(Ce + ((size_t)b * 2304 + kk) * 512 + c4);
;             so[u] = *(const f32x4*)(So + ((size_t)b * 2048 + (use_so[u] ? kk : 1)) * 512 + c4);
;             gz[u] = *(const u32x2*)(Z + (size_t)row * DIN + DG + c4);
; #pragma unroll
;             for (int j = 0; j < 4; ++j) pv[u][j] = bf2f(PQ[((size_t)(b * 512 + c4 + j) * 2) * 4096 + 2048]); }
.LBB0_658:
	s_andn2_b64 vcc, exec, s[36:37]
	s_cbranch_vccnz .LBB0_738
	s_mov_b64 s[36:37], s[0:1]
	s_mov_b32 s3, s70
	v_mov_b32 v0, v147
	s_nop 0
	v_lshl_add_u32 v19, s3, 9, v0
	v_cmp_gt_i32_e32 vcc, s10, v19
	s_and_saveexec_b64 s[46:47], vcc
	s_cbranch_execz .LBB0_684
	s_load_dwordx2 s[48:49], s[36:37], 0x90
	v_lshlrev_b32_e32 v0, 2, v0
	v_lshl_add_u32 v21, s3, 11, v0
	s_mov_b64 s[62:63], 0
	s_waitcnt lgkmcnt(0)
	s_add_u32 s50, s48, 0x8d20000
	s_addc_u32 s51, s49, 0
	s_add_u32 s52, s48, 0x9620000
	s_addc_u32 s53, s49, 0
	s_add_u32 s56, s48, 0x12d20000
	s_addc_u32 s57, s49, 0
	s_add_u32 s58, s48, 0x11521000
	s_addc_u32 s59, s49, 0
	s_add_u32 s60, s48, 0x9e20000
	s_addc_u32 s61, s49, 0
	v_and_b32_e32 v208, 0x1fc, v21
	v_mov_b32_e32 v209, 0
	v_lshlrev_b64 v[210:211], 14, v[208:209]
	s_mov_b64 s[26:27], 0x4000
	s_mov_b64 s[54:55], 0x800000
	v_lshl_add_u64 v[210:211], s[58:59], 0, v[210:211]
	global_load_ushort v200, v[210:211], off
	v_lshl_add_u64 v[212:213], v[210:211], 0, s[26:27]
	global_load_ushort v201, v[212:213], off
	v_lshl_add_u64 v[212:213], v[212:213], 0, s[26:27]
	global_load_ushort v202, v[212:213], off
	v_lshl_add_u64 v[212:213], v[212:213], 0, s[26:27]
	global_load_ushort v203, v[212:213], off
	v_lshl_add_u64 v[210:211], v[210:211], 0, s[54:55]
	global_load_ushort v204, v[210:211], off
	v_lshl_add_u64 v[212:213], v[210:211], 0, s[26:27]
	global_load_ushort v205, v[212:213], off
	v_lshl_add_u64 v[212:213], v[212:213], 0, s[26:27]
	global_load_ushort v206, v[212:213], off
	v_lshl_add_u64 v[212:213], v[212:213], 0, s[26:27]
	global_load_ushort v207, v[212:213], off
	s_branch .LBB0_664

; __device__ __forceinline__ float bf2f(bf16 b) { return __uint_as_float((unsigned)b << 16); }
; __device__ __forceinline__ void ph_combine(const Params& p_) {
;     ...
;         for (int u = 0; u < 2; ++u) { const int e = e0 + u * nth; act[u] = e < MTOK * DG / 4; const int ee = act[u] ? e : e0;
;             const int row = ee >> 7, c4 = (ee & 127) * 4, b = row >> 12, k = row & 4095, kk = (k <= 2048) ? k : 4096 - k;
;             rowv[u] = row; c4v[u] = c4; kv[u] = k; use_so[u] = (kk != 0 && kk != 2048);
;             ce[u] = (kk == 2048) ? *(const f32x4*)(Ce + (size_t)(2 * 2304 + 2 * 2048) * 512 + b * 512 + c4) : *(const f32x4*)(Ce + ((size_t)b * 2304 + kk) * 512 + c4);
;             so[u] = *(const f32x4*)(So + ((size_t)b * 2048 + (use_so[u] ? kk : 1)) * 512 + c4);
;             gz[u] = *(const u32x2*)(Z + (size_t)row * DIN + DG + c4);
; #pragma unroll
;             for (int j = 0; j < 4; ++j) pv[u][j] = bf2f(PQ[((size_t)(b * 512 + c4 + j) * 2) * 4096 + 2048]); }
.LBB0_664:
	v_ashrrev_i32_e32 v24, 7, v19
	v_and_b32_e32 v0, 0xfff, v24
	s_movk_i32 s3, 0x801
	v_sub_u32_e32 v3, 0x1000, v0
	v_cmp_gt_u32_e64 s[36:37], s3, v0
	v_ashrrev_i32_e32 v2, 19, v19
	v_cmp_ne_u32_e64 s[26:27], 0, v2
	v_and_b32_e32 v22, 0x1fc, v21
	v_cndmask_b32_e64 v6, v3, v0, s[36:37]
	v_cmp_lt_u32_e32 vcc, s68, v0
	v_cmp_ne_u32_e64 s[36:37], s68, v6
	v_lshlrev_b32_e32 v4, 9, v2
	s_and_saveexec_b64 s[12:13], s[36:37]
	s_xor_b64 s[36:37], exec, s[12:13]
	v_mul_i32_i24_e32 v4, 0x900, v2
	v_ashrrev_i32_e32 v5, 31, v4
	v_mov_b32_e32 v7, v1
	v_lshl_add_u64 v[4:5], v[6:7], 0, v[4:5]
	v_lshlrev_b64 v[4:5], 11, v[4:5]
	v_lshl_add_u64 v[4:5], s[50:51], 0, v[4:5]
	v_lshlrev_b32_e32 v0, 2, v22
	v_lshl_add_u64 v[8:9], v[4:5], 0, v[0:1]
	v_lshlrev_b32_e32 v4, 9, v2
	s_andn2_saveexec_b64 s[36:37], s[36:37]
	v_ashrrev_i32_e32 v5, 31, v4
	v_lshl_add_u64 v[8:9], v[4:5], 2, s[60:61]
	v_lshlrev_b32_e32 v0, 2, v22
	v_lshl_add_u64 v[8:9], v[8:9], 0, v[0:1]
	s_or_b64 exec, exec, s[36:37]
	v_and_b32_e32 v0, 0x17ff, v6
	v_ashrrev_i32_e32 v3, 31, v2
	v_lshlrev_b32_e32 v5, 9, v6
	v_cmp_ne_u32_e64 s[42:43], 0, v0
	v_lshlrev_b64 v[2:3], 22, v[2:3]
	v_lshl_add_u64 v[2:3], s[52:53], 0, v[2:3]
	v_cndmask_b32_e64 v0, v196, v5, s[42:43]
	v_lshlrev_b32_e32 v0, 2, v0
	v_lshl_add_u64 v[2:3], v[2:3], 0, v[0:1]
	v_lshlrev_b32_e32 v0, 2, v22
	v_mov_b64_e32 v[6:7], s[48:49]
	v_lshl_add_u64 v[2:3], v[2:3], 0, v[0:1]
	v_mad_i64_i32 v[6:7], s[12:13], v24, s75, v[6:7]
	v_lshlrev_b32_e32 v0, 1, v22
	v_lshl_add_u64 v[6:7], v[6:7], 0, v[0:1]
	s_mov_b32 s3, 0xad20000
	v_add_co_u32_e64 v6, s[36:37], s3, v6
	global_load_dwordx4 v[10:13], v[8:9], off
	s_nop 0
	v_addc_co_u32_e64 v7, s[36:37], 0, v7, s[36:37]
	global_load_dwordx4 v[14:17], v[2:3], off
	global_load_dwordx2 v[28:29], v[6:7], off offset:1024
	v_or_b32_e32 v2, v4, v22
	v_ashrrev_i32_e32 v3, 31, v2
	v_lshlrev_b64 v[4:5], 14, v[2:3]
	v_or_b32_e32 v6, 1, v2
	v_or_b32_e32 v8, 2, v2
	v_or_b32_e32 v2, 3, v2
	v_ashrrev_i32_e32 v7, 31, v6
	v_ashrrev_i32_e32 v9, 31, v8
	v_ashrrev_i32_e32 v3, 31, v2
	v_lshl_add_u64 v[4:5], s[58:59], 0, v[4:5]
	v_lshlrev_b64 v[6:7], 14, v[6:7]
	v_lshlrev_b64 v[8:9], 14, v[8:9]
	v_lshlrev_b64 v[2:3], 14, v[2:3]
	v_lshl_add_u64 v[6:7], s[58:59], 0, v[6:7]
	v_lshl_add_u64 v[8:9], s[58:59], 0, v[8:9]
	v_lshl_add_u64 v[2:3], s[58:59], 0, v[2:3]
	s_nop 0
	s_nop 0
	s_nop 0
	s_nop 0
	v_add_u32_e32 v23, s71, v19
	v_cmp_gt_i32_e64 s[38:39], s10, v23
	s_movk_i32 s3, 0x801
	s_nop 0
	v_cndmask_b32_e64 v0, v19, v23, s[38:39]
	v_ashrrev_i32_e32 v18, 7, v0
	v_lshlrev_b32_e32 v2, 2, v0
	v_ashrrev_i32_e32 v6, 19, v0
	v_cmp_ne_u32_e64 s[54:55], 0, v6
	v_and_b32_e32 v0, 0xfff, v18
	v_and_b32_e32 v20, 0x1fc, v2
	v_sub_u32_e32 v2, 0x1000, v0
	v_cmp_gt_u32_e64 s[40:41], s3, v0
	v_cmp_lt_u32_e64 s[36:37], s68, v0
	v_lshlrev_b32_e32 v30, 9, v6
	v_cndmask_b32_e64 v0, v2, v0, s[40:41]
	v_cmp_ne_u32_e64 s[40:41], s68, v0
	s_and_saveexec_b64 s[12:13], s[40:41]
	s_xor_b64 s[40:41], exec, s[12:13]
	v_mul_i32_i24_e32 v2, 0x900, v6
	v_ashrrev_i32_e32 v3, 31, v2
	v_lshl_add_u64 v[2:3], v[0:1], 0, v[2:3]
	v_lshlrev_b64 v[2:3], 11, v[2:3]
	v_lshl_add_u64 v[2:3], s[50:51], 0, v[2:3]
	v_lshlrev_b32_e32 v4, 2, v20
	v_mov_b32_e32 v5, v1
	v_lshl_add_u64 v[2:3], v[2:3], 0, v[4:5]
	v_lshlrev_b32_e32 v30, 9, v6
	s_andn2_saveexec_b64 s[40:41], s[40:41]
	v_ashrrev_i32_e32 v31, 31, v30
	v_lshl_add_u64 v[2:3], v[30:31], 2, s[60:61]
	v_lshlrev_b32_e32 v4, 2, v20
	v_mov_b32_e32 v5, v1
	v_lshl_add_u64 v[2:3], v[2:3], 0, v[4:5]
	s_or_b64 exec, exec, s[40:41]
	v_and_b32_e32 v4, 0x17ff, v0
	v_or_b32_e32 v38, v30, v20
	v_cmp_ne_u32_e64 s[40:41], 0, v4
	v_ashrrev_i32_e32 v7, 31, v6
	v_lshlrev_b32_e32 v0, 9, v0
	v_or_b32_e32 v32, 1, v38
	v_cndmask_b32_e64 v0, v196, v0, s[40:41]
	v_lshlrev_b64 v[6:7], 22, v[6:7]
	v_ashrrev_i32_e32 v39, 31, v38
	v_ashrrev_i32_e32 v33, 31, v32
	v_lshl_add_u64 v[6:7], s[52:53], 0, v[6:7]
	v_lshlrev_b32_e32 v0, 2, v0
	v_lshlrev_b64 v[30:31], 14, v[38:39]
	v_lshlrev_b64 v[32:33], 14, v[32:33]
	v_lshl_add_u64 v[6:7], v[6:7], 0, v[0:1]
	v_lshlrev_b32_e32 v0, 2, v20
	v_mov_b64_e32 v[26:27], s[48:49]
	v_lshl_add_u64 v[30:31], s[58:59], 0, v[30:31]
	v_lshl_add_u64 v[32:33], s[58:59], 0, v[32:33]
	v_lshl_add_u64 v[6:7], v[6:7], 0, v[0:1]
	v_mad_i64_i32 v[26:27], s[12:13], v18, s75, v[26:27]
	v_lshlrev_b32_e32 v0, 1, v20
	s_nop 0
	v_lshl_add_u64 v[26:27], v[26:27], 0, v[0:1]
	s_nop 0
	v_or_b32_e32 v32, 2, v38
	v_or_b32_e32 v38, 3, v38
	s_mov_b32 s3, 0xad20000
	v_ashrrev_i32_e32 v33, 31, v32
	v_ashrrev_i32_e32 v39, 31, v38
	v_add_co_u32_e64 v26, s[44:45], s3, v26
	v_lshlrev_b64 v[32:33], 14, v[32:33]
	v_lshlrev_b64 v[38:39], 14, v[38:39]
	v_addc_co_u32_e64 v27, s[44:45], 0, v27, s[44:45]
	v_lshl_add_u64 v[32:33], s[58:59], 0, v[32:33]
	v_lshl_add_u64 v[38:39], s[58:59], 0, v[38:39]
	global_load_dwordx4 v[2:5], v[2:3], off
	s_nop 0
	global_load_dwordx4 v[6:9], v[6:7], off
	s_nop 0
	global_load_dwordx2 v[26:27], v[26:27], off offset:1024
	s_nop 0
	s_nop 0
	s_nop 0
	s_nop 0
	s_and_saveexec_b64 s[44:45], s[42:43]
	s_cbranch_execz .LBB0_678
	s_and_saveexec_b64 s[12:13], vcc
	s_xor_b64 s[42:43], exec, s[12:13]
	s_cbranch_execz .LBB0_675
	s_waitcnt vmcnt(0)
	v_pk_add_f32 v[12:13], v[12:13], v[16:17]
	v_pk_add_f32 v[10:11], v[10:11], v[14:15]

; __device__ __forceinline__ unsigned pk2(float lo, float hi) { return f2bf(lo) | (f2bf(hi) << 16); }
; __device__ __forceinline__ float bflo(unsigned u) { return __uint_as_float(u << 16); }
; __device__ __forceinline__ float bfhi(unsigned u) { return __uint_as_float(u & 0xffff0000u); }
; __device__ __forceinline__ float silu_f(float v) { return v / (1.f + __expf(-v)); }
; __device__ __forceinline__ void ph_combine(const Params& p_) {
;     ...
; #pragma unroll
;         for (int u = 0; u < 2; ++u) if (act[u]) { f32x4 s = ce[u];
;             if (use_so[u]) s = (kv[u] <= 2048) ? s - so[u] : s + so[u];
;             const float alt = (kv[u] & 1) ? -1.f : 1.f;
; #pragma unroll
;             for (int j = 0; j < 4; ++j) s[j] += alt * pv[u][j];
;             u32x2 w; w.x = pk2(s[0] * silu_f(bflo(gz[u].x)), s[1] * silu_f(bfhi(gz[u].x))); w.y = pk2(s[2] * silu_f(bflo(gz[u].y)), s[3] * silu_f(bfhi(gz[u].y)));
;             *(u32x2*)(CAT + (size_t)rowv[u] * DM + c4v[u]) = w; }
.LBB0_678:
	s_or_b64 exec, exec, s[44:45]
	s_waitcnt vmcnt(0)
	v_cndmask_b32_e64 v35, v200, v204, s[26:27]
	v_cndmask_b32_e64 v34, v201, v205, s[26:27]
	v_cndmask_b32_e64 v37, v202, v206, s[26:27]
	v_cndmask_b32_e64 v36, v203, v207, s[26:27]
	v_cndmask_b32_e64 v30, v200, v204, s[54:55]
	v_cndmask_b32_e64 v31, v201, v205, s[54:55]
	v_cndmask_b32_e64 v32, v202, v206, s[54:55]
	v_cndmask_b32_e64 v33, v203, v207, s[54:55]
	v_and_b32_e32 v15, 0x80, v19
	v_lshlrev_b32_e32 v0, 16, v35
	v_lshlrev_b32_e32 v14, 16, v37
	v_cmp_eq_u32_e64 s[42:43], 0, v15
	v_lshlrev_b32_e32 v34, 16, v34
	v_lshlrev_b32_e32 v35, 16, v36
	v_lshlrev_b32_e32 v36, 16, v28
	v_cndmask_b32_e64 v15, -v14, v14, s[42:43]
	v_cndmask_b32_e64 v14, -v0, v0, s[42:43]
	v_mov_b32_e32 v16, v10
	v_mov_b32_e32 v17, v12
	v_and_b32_e32 v28, 0xffff0000, v28
	v_pk_add_f32 v[14:15], v[14:15], v[16:17]
	v_cndmask_b32_e64 v17, -v35, v35, s[42:43]
	v_cndmask_b32_e64 v16, -v34, v34, s[42:43]
	v_mov_b32_e32 v12, v11
	v_mul_f32_e32 v0, 0xbfb8aa3b, v36
	v_lshlrev_b32_e32 v19, 16, v29
	v_pk_add_f32 v[10:11], v[16:17], v[12:13]
	v_exp_f32_e32 v12, v0
	v_mul_f32_e32 v0, 0xbfb8aa3b, v28
	v_exp_f32_e32 v16, v0
	v_mul_f32_e32 v0, 0xbfb8aa3b, v19
	v_exp_f32_e32 v13, v0
	v_and_b32_e32 v29, 0xffff0000, v29
	v_ashrrev_i32_e32 v25, 31, v24
	v_pk_add_f32 v[12:13], v[12:13], 1.0 op_sel_hi:[1,0]
	s_nop 0
	v_div_scale_f32 v0, s[12:13], v13, v13, v19
	v_rcp_f32_e32 v17, v0
	s_nop 0
	v_fma_f32 v34, -v0, v17, 1.0
	v_fmac_f32_e32 v17, v34, v17
	v_div_scale_f32 v34, vcc, v19, v13, v19
	v_mul_f32_e32 v35, v34, v17
	v_fma_f32 v37, -v0, v35, v34
	v_fmac_f32_e32 v35, v37, v17
	v_fma_f32 v0, -v0, v35, v34
	v_div_fmas_f32 v0, v0, v17, v35
	v_div_fixup_f32 v13, v0, v13, v19
	v_div_scale_f32 v0, s[12:13], v12, v12, v36
	v_rcp_f32_e32 v17, v0
	s_nop 0
	v_fma_f32 v19, -v0, v17, 1.0
	v_fmac_f32_e32 v17, v19, v17
	v_div_scale_f32 v19, vcc, v36, v12, v36
	v_mul_f32_e32 v34, v19, v17
	v_fma_f32 v35, -v0, v34, v19
	v_fmac_f32_e32 v34, v35, v17
	v_fma_f32 v0, -v0, v34, v19
	v_div_fmas_f32 v0, v0, v17, v34
	v_div_fixup_f32 v12, v0, v12, v36
	v_mul_f32_e32 v0, 0xbfb8aa3b, v29
	v_exp_f32_e32 v17, v0
	v_pk_mul_f32 v[12:13], v[12:13], v[14:15]
	v_pk_add_f32 v[14:15], v[16:17], 1.0 op_sel_hi:[1,0]
	s_nop 0
	v_div_scale_f32 v0, s[12:13], v15, v15, v29
	v_rcp_f32_e32 v16, v0
	s_nop 0
	v_fma_f32 v17, -v0, v16, 1.0
	v_fmac_f32_e32 v16, v17, v16
	v_div_scale_f32 v17, vcc, v29, v15, v29
	v_mul_f32_e32 v19, v17, v16
	v_fma_f32 v34, -v0, v19, v17
	v_fmac_f32_e32 v19, v34, v16
	v_fma_f32 v0, -v0, v19, v17
	v_div_fmas_f32 v0, v0, v16, v19
	v_div_fixup_f32 v15, v0, v15, v29
	v_div_scale_f32 v0, s[12:13], v14, v14, v28
	v_rcp_f32_e32 v16, v0
	s_nop 0
	v_fma_f32 v17, -v0, v16, 1.0
	v_fmac_f32_e32 v16, v17, v16
	v_div_scale_f32 v17, vcc, v28, v14, v28
	v_mul_f32_e32 v19, v17, v16
	v_fma_f32 v29, -v0, v19, v17
	v_fmac_f32_e32 v19, v29, v16
	v_fma_f32 v0, -v0, v19, v17
	v_div_fmas_f32 v0, v0, v16, v19
	v_div_fixup_f32 v14, v0, v14, v28
	v_pk_mul_f32 v[10:11], v[14:15], v[10:11]
	v_and_b32_sdwa v14, v12, v179 dst_sel:DWORD dst_unused:UNUSED_PAD src0_sel:WORD_1 src1_sel:DWORD
	v_and_b32_sdwa v0, v13, v179 dst_sel:DWORD dst_unused:UNUSED_PAD src0_sel:WORD_1 src1_sel:DWORD
	v_add3_u32 v12, v12, v14, s14
	v_and_b32_sdwa v14, v10, v179 dst_sel:DWORD dst_unused:UNUSED_PAD src0_sel:WORD_1 src1_sel:DWORD
	v_add3_u32 v0, v13, v0, s14
	v_and_b32_sdwa v13, v11, v179 dst_sel:DWORD dst_unused:UNUSED_PAD src0_sel:WORD_1 src1_sel:DWORD
	v_add3_u32 v10, v10, v14, s14
	v_add3_u32 v11, v11, v13, s14
	v_and_b32_e32 v10, 0xffff0000, v10
	v_and_b32_e32 v11, 0xffff0000, v11
	v_or_b32_sdwa v10, v10, v12 dst_sel:DWORD dst_unused:UNUSED_PAD src0_sel:DWORD src1_sel:WORD_1
	v_lshlrev_b64 v[12:13], 12, v[24:25]
	v_or_b32_sdwa v11, v11, v0 dst_sel:DWORD dst_unused:UNUSED_PAD src0_sel:DWORD src1_sel:WORD_1
	v_lshl_add_u64 v[12:13], s[56:57], 0, v[12:13]
	v_lshlrev_b32_e32 v0, 1, v22
	v_lshl_add_u64 v[12:13], v[12:13], 0, v[0:1]
	global_store_dwordx2 v[12:13], v[10:11], off
	s_and_saveexec_b64 s[44:45], s[38:39]
	s_cbranch_execz .LBB0_663
	s_and_saveexec_b64 s[38:39], s[40:41]
	s_cbranch_execz .LBB0_662
	s_and_saveexec_b64 s[12:13], s[36:37]
	s_xor_b64 s[36:37], exec, s[12:13]
	v_pk_add_f32 v[4:5], v[4:5], v[8:9]
	v_pk_add_f32 v[2:3], v[2:3], v[6:7]
	s_andn2_saveexec_b64 s[36:37], s[36:37]
	s_cbranch_execz .LBB0_661
	v_sub_f32_e32 v5, v5, v9
	v_sub_f32_e32 v4, v4, v8
	v_sub_f32_e32 v3, v3, v7
	v_sub_f32_e32 v2, v2, v6
	s_branch .LBB0_661
